# t15 with the first 2 V DMAs issued at the PV loop top (before the P reads), none in the head, 6 behind MFMAs 2..12
# speedup vs baseline: 1.0153x; 1.0006x over previous
; #define SBAR() __builtin_amdgcn_sched_barrier(0)
; #define RS_BAR() do { asm volatile("s_waitcnt lgkmcnt(0)" ::: "memory"); __builtin_amdgcn_s_barrier(); asm volatile("" ::: "memory"); } while (0)
; #define VM0() asm volatile("s_waitcnt vmcnt(0)" ::: "memory")
; #define VM0() asm volatile("s_waitcnt vmcnt(0)" ::: "memory")
; #define VMMA(OD, F) do { OD = __builtin_amdgcn_mfma_f32_32x32x16_bf16(pa0, PKF(F[0], F[1]), OD, 0, 0, 0); OD = __builtin_amdgcn_mfma_f32_32x32x16_bf16(pa1, PKF(F[2], F[3]), OD, 0, 0, 0); \
;       OD = __builtin_amdgcn_mfma_f32_32x32x16_bf16(pa2, PKF(F[4], F[5]), OD, 0, 0, 0); OD = __builtin_amdgcn_mfma_f32_32x32x16_bf16(pa3, PKF(F[6], F[7]), OD, 0, 0, 0); } while (0)
; #define LW(n) do { asm volatile("s_waitcnt lgkmcnt(" #n ")" ::: "memory"); SBAR(); } while (0)
; template <class Epi>
; __device__ __forceinline__ void attn_rs_body(const bf16* __restrict__ Qb, const bf16* __restrict__ Kc, const bf16* __restrict__ V0c, const bf16* __restrict__ V1c, int NT, char* lds, const Epi& epi) {
;     ...
;       const int vb = vb0 + b * 32768;
;       s16x4 fa[8], fb[8];
;       { const int tv = j < NT ? j : NT - 1; VDMA(tv, b ^ 1); }
;       asm volatile("s_waitcnt lgkmcnt(0)" ::: "memory"); SBAR();
;       VRD(fa, 0, 0); VRD(fb, 1, 0); LW(8); VMMA(o[0], fa);
;       VRD(fa, 2, 0); LW(8); VMMA(o[1], fb);
;       VRD(fb, 3, 0); LW(8); VMMA(o[2], fa);
;       VRD(fa, 0, 1); LW(8); VMMA(o[3], fb);
;       VRD(fb, 1, 1); LW(8); VMMA(o[4], fa);
;       VRD(fa, 2, 1); LW(8); VMMA(o[5], fb);
;       VRD(fb, 3, 1); LW(8); VMMA(o[6], fa);
;       LW(0); VMMA(o[7], fb);
;       VM0(); RS_BAR();
.LBB0_500:
	s_lshl_b32 s72, s72, 15
	v_lshl_add_u64 v[244:245], v[176:177], 0, s[48:49]
	s_add_i32 s72, s51, s72
	v_lshl_add_u64 v[246:247], v[174:175], 0, s[48:49]
	v_lshl_add_u32 v0, s71, 15, v182
	s_waitcnt lgkmcnt(0)
	ds_read_b64_tr_b16 v[146:147], v0 offset:0
	ds_read_b64_tr_b16 v[148:149], v0 offset:0x800
	ds_read_b64_tr_b16 v[150:151], v0 offset:0x1000
	ds_read_b64_tr_b16 v[152:153], v0 offset:0x1800
	ds_read_b64_tr_b16 v[154:155], v0 offset:0x2000
	ds_read_b64_tr_b16 v[156:157], v0 offset:0x2800
	ds_read_b64_tr_b16 v[158:159], v0 offset:0x3000
	ds_read_b64_tr_b16 v[160:161], v0 offset:0x3800
	ds_read_b64_tr_b16 v[184:185], v0 offset:0x200
	ds_read_b64_tr_b16 v[186:187], v0 offset:0xa00
	ds_read_b64_tr_b16 v[188:189], v0 offset:0x1200
	ds_read_b64_tr_b16 v[190:191], v0 offset:0x1a00
	ds_read_b64_tr_b16 v[192:193], v0 offset:0x2200
	ds_read_b64_tr_b16 v[194:195], v0 offset:0x2a00
	ds_read_b64_tr_b16 v[196:197], v0 offset:0x3200
	ds_read_b64_tr_b16 v[198:199], v0 offset:0x3a00
	s_waitcnt lgkmcnt(8)
	s_nop 0
	v_mfma_f32_32x32x16_bf16 v[114:129], v[142:145], v[146:149], v[114:129]
	ds_read_b64_tr_b16 v[146:147], v0 offset:0x400
	ds_read_b64_tr_b16 v[148:149], v0 offset:0xc00
	v_mfma_f32_32x32x16_bf16 v[114:129], v[138:141], v[150:153], v[114:129]
	ds_read_b64_tr_b16 v[150:151], v0 offset:0x1400
	ds_read_b64_tr_b16 v[152:153], v0 offset:0x1c00
	s_add_i32 m0, s72, 0x8400
	v_lshl_add_u64 v[248:249], v[244:245], 0, s[16:17]
	global_load_lds_dwordx4 v[248:249], off
	v_mfma_f32_32x32x16_bf16 v[114:129], v[134:137], v[154:157], v[114:129]
	ds_read_b64_tr_b16 v[154:155], v0 offset:0x2400
	ds_read_b64_tr_b16 v[156:157], v0 offset:0x2c00
	v_mfma_f32_32x32x16_bf16 v[114:129], v[130:133], v[158:161], v[114:129]
	ds_read_b64_tr_b16 v[158:159], v0 offset:0x3400
	ds_read_b64_tr_b16 v[160:161], v0 offset:0x3c00
	s_waitcnt lgkmcnt(8)
	s_add_i32 m0, s72, 0xc400
	v_lshl_add_u64 v[250:251], v[244:245], 0, s[18:19]
	global_load_lds_dwordx4 v[250:251], off
	v_mfma_f32_32x32x16_bf16 v[98:113], v[142:145], v[184:187], v[98:113]
	ds_read_b64_tr_b16 v[184:185], v0 offset:0x600
	ds_read_b64_tr_b16 v[186:187], v0 offset:0xe00
	v_mfma_f32_32x32x16_bf16 v[98:113], v[138:141], v[188:191], v[98:113]
	ds_read_b64_tr_b16 v[188:189], v0 offset:0x1600
	ds_read_b64_tr_b16 v[190:191], v0 offset:0x1e00
	s_add_i32 m0, s72, 0x8800
	v_lshl_add_u64 v[248:249], v[246:247], 0, s[12:13]
	global_load_lds_dwordx4 v[248:249], off
	v_mfma_f32_32x32x16_bf16 v[98:113], v[134:137], v[192:195], v[98:113]
	ds_read_b64_tr_b16 v[192:193], v0 offset:0x2600
	ds_read_b64_tr_b16 v[194:195], v0 offset:0x2e00
	v_mfma_f32_32x32x16_bf16 v[98:113], v[130:133], v[196:199], v[98:113]
	ds_read_b64_tr_b16 v[196:197], v0 offset:0x3600
	ds_read_b64_tr_b16 v[198:199], v0 offset:0x3e00
	s_waitcnt lgkmcnt(8)
	s_add_i32 m0, s72, 0xc800
	v_lshl_add_u64 v[250:251], v[246:247], 0, s[14:15]
	global_load_lds_dwordx4 v[250:251], off
	v_mfma_f32_32x32x16_bf16 v[82:97], v[142:145], v[146:149], v[82:97]
	ds_read_b64_tr_b16 v[146:147], v0 offset:0x4000
	ds_read_b64_tr_b16 v[148:149], v0 offset:0x4800
	v_mfma_f32_32x32x16_bf16 v[82:97], v[138:141], v[150:153], v[82:97]
	ds_read_b64_tr_b16 v[150:151], v0 offset:0x5000
	ds_read_b64_tr_b16 v[152:153], v0 offset:0x5800
	s_add_i32 m0, s72, 0x8c00
	v_lshl_add_u64 v[248:249], v[246:247], 0, s[16:17]
	global_load_lds_dwordx4 v[248:249], off
	v_mfma_f32_32x32x16_bf16 v[82:97], v[134:137], v[154:157], v[82:97]
	ds_read_b64_tr_b16 v[154:155], v0 offset:0x6000
	ds_read_b64_tr_b16 v[156:157], v0 offset:0x6800
	v_mfma_f32_32x32x16_bf16 v[82:97], v[130:133], v[158:161], v[82:97]
	ds_read_b64_tr_b16 v[158:159], v0 offset:0x7000
	ds_read_b64_tr_b16 v[160:161], v0 offset:0x7800
	s_waitcnt lgkmcnt(8)
	s_add_i32 m0, s72, 0xcc00
	v_lshl_add_u64 v[250:251], v[246:247], 0, s[18:19]
	global_load_lds_dwordx4 v[250:251], off
	v_mfma_f32_32x32x16_bf16 v[66:81], v[142:145], v[184:187], v[66:81]
	ds_read_b64_tr_b16 v[184:185], v0 offset:0x4200
	ds_read_b64_tr_b16 v[186:187], v0 offset:0x4a00
	v_mfma_f32_32x32x16_bf16 v[66:81], v[138:141], v[188:191], v[66:81]
	ds_read_b64_tr_b16 v[188:189], v0 offset:0x5200
	ds_read_b64_tr_b16 v[190:191], v0 offset:0x5a00
	v_mfma_f32_32x32x16_bf16 v[66:81], v[134:137], v[192:195], v[66:81]
	ds_read_b64_tr_b16 v[192:193], v0 offset:0x6200
	ds_read_b64_tr_b16 v[194:195], v0 offset:0x6a00
	v_mfma_f32_32x32x16_bf16 v[66:81], v[130:133], v[196:199], v[66:81]
	ds_read_b64_tr_b16 v[196:197], v0 offset:0x7200
	ds_read_b64_tr_b16 v[198:199], v0 offset:0x7a00
	s_waitcnt lgkmcnt(8)
	v_mfma_f32_32x32x16_bf16 v[50:65], v[142:145], v[146:149], v[50:65]
	ds_read_b64_tr_b16 v[146:147], v0 offset:0x4400
	ds_read_b64_tr_b16 v[148:149], v0 offset:0x4c00
	v_mfma_f32_32x32x16_bf16 v[50:65], v[138:141], v[150:153], v[50:65]
	ds_read_b64_tr_b16 v[150:151], v0 offset:0x5400
	ds_read_b64_tr_b16 v[152:153], v0 offset:0x5c00
	v_mfma_f32_32x32x16_bf16 v[50:65], v[134:137], v[154:157], v[50:65]
	ds_read_b64_tr_b16 v[154:155], v0 offset:0x6400
	ds_read_b64_tr_b16 v[156:157], v0 offset:0x6c00
	v_mfma_f32_32x32x16_bf16 v[50:65], v[130:133], v[158:161], v[50:65]
	ds_read_b64_tr_b16 v[158:159], v0 offset:0x7400
	ds_read_b64_tr_b16 v[160:161], v0 offset:0x7c00
	s_waitcnt lgkmcnt(8)
	v_mfma_f32_32x32x16_bf16 v[34:49], v[142:145], v[184:187], v[34:49]
	ds_read_b64_tr_b16 v[184:185], v0 offset:0x4600
	ds_read_b64_tr_b16 v[186:187], v0 offset:0x4e00
	v_mfma_f32_32x32x16_bf16 v[34:49], v[138:141], v[188:191], v[34:49]
	ds_read_b64_tr_b16 v[188:189], v0 offset:0x5600
	ds_read_b64_tr_b16 v[190:191], v0 offset:0x5e00
	v_mfma_f32_32x32x16_bf16 v[34:49], v[134:137], v[192:195], v[34:49]
	ds_read_b64_tr_b16 v[192:193], v0 offset:0x6600
	ds_read_b64_tr_b16 v[194:195], v0 offset:0x6e00
	v_mfma_f32_32x32x16_bf16 v[34:49], v[130:133], v[196:199], v[34:49]
	ds_read_b64_tr_b16 v[196:197], v0 offset:0x7600
	ds_read_b64_tr_b16 v[198:199], v0 offset:0x7e00
	s_waitcnt lgkmcnt(8)
	s_waitcnt lgkmcnt(0)
	s_waitcnt vmcnt(0)
	s_add_i32 s70, s70, 1
	s_waitcnt lgkmcnt(0)
	s_barrier
	s_add_u32 s48, s48, 0x4000
	s_addc_u32 s49, s49, 0
	v_mfma_f32_32x32x16_bf16 v[18:33], v[142:145], v[146:149], v[18:33]
	v_mfma_f32_32x32x16_bf16 v[2:17], v[142:145], v[184:187], v[2:17]
	v_mfma_f32_32x32x16_bf16 v[18:33], v[138:141], v[150:153], v[18:33]
	v_mfma_f32_32x32x16_bf16 v[2:17], v[138:141], v[188:191], v[2:17]
	v_mfma_f32_32x32x16_bf16 v[18:33], v[134:137], v[154:157], v[18:33]
	v_mfma_f32_32x32x16_bf16 v[2:17], v[134:137], v[192:195], v[2:17]
	s_cmp_eq_u32 s48, 0x1fc000
	v_mfma_f32_32x32x16_bf16 v[18:33], v[130:133], v[158:161], v[18:33]
	v_mfma_f32_32x32x16_bf16 v[2:17], v[130:133], v[196:199], v[2:17]
	s_cbranch_scc1 .LBB0_503
; __device__ __forceinline__ int crow(int r, int hi) { return (r & 3) + 8 * (r >> 2) + 4 * hi; }
; template <class Epi>
; __device__ __forceinline__ void attn_rs_body(const bf16* __restrict__ Qb, const bf16* __restrict__ Kc, const bf16* __restrict__ V0c, const bf16* __restrict__ V1c, int NT, char* lds, const Epi& epi) {
;     ...
;     for (int j = 1; j <= NT; ++j) {
;       const int b = (j - 1) & 1;
;       const char* Pb = Pl + b * 16384;
;       const bf16x8 pa0 = *(const bf16x8*)(Pb), pa1 = *(const bf16x8*)(Pb + 1024), pa2 = *(const bf16x8*)(Pb + 2048), pa3 = *(const bf16x8*)(Pb + 3072);
;       const float flag = al[b * 256 + 32];
;       if (__builtin_amdgcn_readfirstlane(__float_as_uint(flag)) != 0u) {
;         float av[16];
; #pragma unroll
;         for (int r = 0; r < 16; ++r) av[r] = al[b * 256 + crow(r, hi)];
; #pragma unroll
;         for (int d = 0; d < 8; ++d)
; #pragma unroll
;           for (int r = 0; r < 16; ++r) o[d][r] *= av[r];
;       }
;       const int vb = vb0 + b * 32768;
;       s16x4 fa[8], fb[8];
;       { const int tv = j < NT ? j : NT - 1; VDMA(tv, b ^ 1); }
.LBB0_501:
	s_and_b32 s72, s70, 1
	s_xor_b32 s71, s72, 1
	s_lshl_b32 s97, s72, 15
	s_add_i32 s97, s51, s97
	v_lshl_add_u64 v[244:245], v[176:177], 0, s[48:49]
	s_add_i32 m0, s97, 0x8000
	v_lshl_add_u64 v[248:249], v[244:245], 0, s[12:13]
	global_load_lds_dwordx4 v[248:249], off
	s_add_i32 m0, s97, 0xc000
	v_lshl_add_u64 v[250:251], v[244:245], 0, s[14:15]
	global_load_lds_dwordx4 v[250:251], off
	s_lshl_b32 s73, s71, 10
	s_add_i32 s73, s65, s73
	v_mov_b32_e32 v130, s73
	v_lshl_add_u32 v0, s71, 14, v179
	ds_read_b32 v146, v130 offset:128
	ds_read_b128 v[142:145], v0
	ds_read_b128 v[138:141], v0 offset:1024
	ds_read_b128 v[134:137], v0 offset:2048
	ds_read_b128 v[130:133], v0 offset:3072
	s_waitcnt lgkmcnt(0)
	v_readfirstlane_b32 s74, v146
	s_cmp_eq_u32 s74, 0
	s_cbranch_scc1 .LBB0_500
	v_add_u32_e32 v0, s73, v164
	ds_read_b128 v[158:161], v0 offset:96
	ds_read_b128 v[154:157], v0 offset:64
	ds_read_b128 v[150:153], v0 offset:32
	ds_read_b128 v[146:149], v0
	s_waitcnt lgkmcnt(0)
	v_pk_mul_f32 v[126:127], v[126:127], v[158:159]
	v_pk_mul_f32 v[122:123], v[122:123], v[154:155]
	v_pk_mul_f32 v[118:119], v[118:119], v[150:151]
	v_pk_mul_f32 v[128:129], v[128:129], v[160:161]
	v_pk_mul_f32 v[124:125], v[124:125], v[156:157]
	v_pk_mul_f32 v[120:121], v[120:121], v[152:153]
	v_pk_mul_f32 v[116:117], v[116:117], v[148:149]
	v_pk_mul_f32 v[114:115], v[114:115], v[146:147]
	v_pk_mul_f32 v[110:111], v[110:111], v[158:159]
	v_pk_mul_f32 v[106:107], v[106:107], v[154:155]
	v_pk_mul_f32 v[102:103], v[102:103], v[150:151]
	v_pk_mul_f32 v[112:113], v[112:113], v[160:161]
	v_pk_mul_f32 v[108:109], v[108:109], v[156:157]
	v_pk_mul_f32 v[104:105], v[104:105], v[152:153]
	v_pk_mul_f32 v[100:101], v[100:101], v[148:149]
	v_pk_mul_f32 v[98:99], v[98:99], v[146:147]
	v_pk_mul_f32 v[94:95], v[94:95], v[158:159]
	v_pk_mul_f32 v[90:91], v[90:91], v[154:155]
	v_pk_mul_f32 v[86:87], v[86:87], v[150:151]
	v_pk_mul_f32 v[96:97], v[96:97], v[160:161]
	v_pk_mul_f32 v[92:93], v[92:93], v[156:157]
	v_pk_mul_f32 v[88:89], v[88:89], v[152:153]
	v_pk_mul_f32 v[84:85], v[84:85], v[148:149]
	v_pk_mul_f32 v[82:83], v[82:83], v[146:147]
	v_pk_mul_f32 v[78:79], v[78:79], v[158:159]
	v_pk_mul_f32 v[74:75], v[74:75], v[154:155]
	v_pk_mul_f32 v[70:71], v[70:71], v[150:151]
	v_pk_mul_f32 v[80:81], v[80:81], v[160:161]
	v_pk_mul_f32 v[76:77], v[76:77], v[156:157]
	v_pk_mul_f32 v[72:73], v[72:73], v[152:153]
	v_pk_mul_f32 v[68:69], v[68:69], v[148:149]
	v_pk_mul_f32 v[66:67], v[66:67], v[146:147]
	v_pk_mul_f32 v[62:63], v[62:63], v[158:159]
	v_pk_mul_f32 v[58:59], v[58:59], v[154:155]
	v_pk_mul_f32 v[54:55], v[54:55], v[150:151]
	v_pk_mul_f32 v[64:65], v[64:65], v[160:161]
	v_pk_mul_f32 v[60:61], v[60:61], v[156:157]
	v_pk_mul_f32 v[56:57], v[56:57], v[152:153]
	v_pk_mul_f32 v[52:53], v[52:53], v[148:149]
	v_pk_mul_f32 v[50:51], v[50:51], v[146:147]
	v_pk_mul_f32 v[46:47], v[46:47], v[158:159]
	v_pk_mul_f32 v[42:43], v[42:43], v[154:155]
	v_pk_mul_f32 v[38:39], v[38:39], v[150:151]
	v_pk_mul_f32 v[48:49], v[48:49], v[160:161]
	v_pk_mul_f32 v[44:45], v[44:45], v[156:157]
	v_pk_mul_f32 v[40:41], v[40:41], v[152:153]
	v_pk_mul_f32 v[36:37], v[36:37], v[148:149]
	v_pk_mul_f32 v[34:35], v[34:35], v[146:147]
	v_pk_mul_f32 v[30:31], v[30:31], v[158:159]
	v_pk_mul_f32 v[26:27], v[26:27], v[154:155]
	v_pk_mul_f32 v[22:23], v[22:23], v[150:151]
	v_pk_mul_f32 v[32:33], v[32:33], v[160:161]
	v_pk_mul_f32 v[28:29], v[28:29], v[156:157]
	v_pk_mul_f32 v[24:25], v[24:25], v[152:153]
	v_pk_mul_f32 v[20:21], v[20:21], v[148:149]
	v_pk_mul_f32 v[18:19], v[18:19], v[146:147]
	v_pk_mul_f32 v[14:15], v[14:15], v[158:159]
	v_pk_mul_f32 v[10:11], v[10:11], v[154:155]
	v_pk_mul_f32 v[6:7], v[6:7], v[150:151]
	v_pk_mul_f32 v[16:17], v[16:17], v[160:161]
	v_pk_mul_f32 v[12:13], v[12:13], v[156:157]
	v_pk_mul_f32 v[8:9], v[8:9], v[152:153]
	v_pk_mul_f32 v[4:5], v[4:5], v[148:149]
	v_pk_mul_f32 v[2:3], v[2:3], v[146:147]
	s_branch .LBB0_500
